# FFN-up GEMM K-loop: 16 per-load 64-bit VALU address adds replaced by SGPR-base + 32-bit lane offset LDS-DMA addressing
# speedup vs baseline: 1.0291x; 1.0019x over previous
.LBB0_1574:
	s_waitcnt lgkmcnt(0)
	s_ashr_i32 s19, s18, 31
	s_lshl_b64 s[20:21], s[18:19], 19
	s_add_u32 s20, s44, s20
	s_addc_u32 s21, s45, s21
	s_and_b64 s[22:23], s[4:5], exec
	s_cselect_b32 s19, s21, s27
	s_cselect_b32 s55, s20, s26
	s_ashr_i32 s17, s16, 31
	s_lshl_b64 s[22:23], s[16:17], 19
	s_add_u32 s22, s36, s22
	s_addc_u32 s23, s37, s23
	s_and_b64 s[30:31], s[4:5], exec
	s_cselect_b32 s17, s23, s29
	s_cselect_b32 s56, s22, s28
	s_add_u32 s26, s26, 0x40080
	s_addc_u32 s27, s27, 0
	s_add_u32 s57, s28, 0x100
	v_mov_b32_e32 v4, 0
	s_addc_u32 s58, s29, 0
	s_mov_b32 s59, -2
	v_mov_b32_e32 v5, v4
	v_mov_b32_e32 v6, v4
	v_mov_b32_e32 v7, v4
	v_mov_b32_e32 v12, v4
	v_mov_b32_e32 v13, v4
	v_mov_b32_e32 v14, v4
	v_mov_b32_e32 v15, v4
	v_mov_b32_e32 v20, v4
	v_mov_b32_e32 v21, v4
	v_mov_b32_e32 v22, v4
	v_mov_b32_e32 v23, v4
	v_mov_b32_e32 v28, v4
	v_mov_b32_e32 v29, v4
	v_mov_b32_e32 v30, v4
	v_mov_b32_e32 v31, v4
	v_mov_b32_e32 v36, v4
	v_mov_b32_e32 v37, v4
	v_mov_b32_e32 v38, v4
	v_mov_b32_e32 v39, v4
	v_mov_b32_e32 v44, v4
	v_mov_b32_e32 v45, v4
	v_mov_b32_e32 v46, v4
	v_mov_b32_e32 v47, v4
	v_mov_b32_e32 v52, v4
	v_mov_b32_e32 v53, v4
	v_mov_b32_e32 v54, v4
	v_mov_b32_e32 v55, v4
	v_mov_b32_e32 v60, v4
	v_mov_b32_e32 v61, v4
	v_mov_b32_e32 v62, v4
	v_mov_b32_e32 v63, v4
	v_mov_b32_e32 v8, v4
	v_mov_b32_e32 v9, v4
	v_mov_b32_e32 v10, v4
	v_mov_b32_e32 v11, v4
	v_mov_b32_e32 v16, v4
	v_mov_b32_e32 v17, v4
	v_mov_b32_e32 v18, v4
	v_mov_b32_e32 v19, v4
	v_mov_b32_e32 v24, v4
	v_mov_b32_e32 v25, v4
	v_mov_b32_e32 v26, v4
	v_mov_b32_e32 v27, v4
	v_mov_b32_e32 v32, v4
	v_mov_b32_e32 v33, v4
	v_mov_b32_e32 v34, v4
	v_mov_b32_e32 v35, v4
	v_mov_b32_e32 v40, v4
	v_mov_b32_e32 v41, v4
	v_mov_b32_e32 v42, v4
	v_mov_b32_e32 v43, v4
	v_mov_b32_e32 v48, v4
	v_mov_b32_e32 v49, v4
	v_mov_b32_e32 v50, v4
	v_mov_b32_e32 v51, v4
	v_mov_b32_e32 v56, v4
	v_mov_b32_e32 v57, v4
	v_mov_b32_e32 v58, v4
	v_mov_b32_e32 v59, v4
	v_mov_b32_e32 v64, v4
	v_mov_b32_e32 v65, v4
	v_mov_b32_e32 v66, v4
	v_mov_b32_e32 v67, v4
	v_mov_b32_e32 v68, v4
	v_mov_b32_e32 v69, v4
	v_mov_b32_e32 v70, v4
	v_mov_b32_e32 v71, v4
	v_mov_b32_e32 v76, v4
	v_mov_b32_e32 v77, v4
	v_mov_b32_e32 v78, v4
	v_mov_b32_e32 v79, v4
	v_mov_b32_e32 v84, v4
	v_mov_b32_e32 v85, v4
	v_mov_b32_e32 v86, v4
	v_mov_b32_e32 v87, v4
	v_mov_b32_e32 v92, v4
	v_mov_b32_e32 v93, v4
	v_mov_b32_e32 v94, v4
	v_mov_b32_e32 v95, v4
	v_mov_b32_e32 v100, v4
	v_mov_b32_e32 v101, v4
	v_mov_b32_e32 v102, v4
	v_mov_b32_e32 v103, v4
	v_mov_b32_e32 v108, v4
	v_mov_b32_e32 v109, v4
	v_mov_b32_e32 v110, v4
	v_mov_b32_e32 v111, v4
	v_mov_b32_e32 v116, v4
	v_mov_b32_e32 v117, v4
	v_mov_b32_e32 v118, v4
	v_mov_b32_e32 v119, v4
	v_mov_b32_e32 v124, v4
	v_mov_b32_e32 v125, v4
	v_mov_b32_e32 v126, v4
	v_mov_b32_e32 v127, v4
	v_mov_b32_e32 v72, v4
	v_mov_b32_e32 v73, v4
	v_mov_b32_e32 v74, v4
	v_mov_b32_e32 v75, v4
	v_mov_b32_e32 v80, v4
	v_mov_b32_e32 v81, v4
	v_mov_b32_e32 v82, v4
	v_mov_b32_e32 v83, v4
	v_mov_b32_e32 v88, v4
	v_mov_b32_e32 v89, v4
	v_mov_b32_e32 v90, v4
	v_mov_b32_e32 v91, v4
	v_mov_b32_e32 v96, v4
	v_mov_b32_e32 v97, v4
	v_mov_b32_e32 v98, v4
	v_mov_b32_e32 v99, v4
	v_mov_b32_e32 v104, v4
	v_mov_b32_e32 v105, v4
	v_mov_b32_e32 v106, v4
	v_mov_b32_e32 v107, v4
	v_mov_b32_e32 v112, v4
	v_mov_b32_e32 v113, v4
	v_mov_b32_e32 v114, v4
	v_mov_b32_e32 v115, v4
	v_mov_b32_e32 v120, v4
	v_mov_b32_e32 v121, v4
	v_mov_b32_e32 v122, v4
	v_mov_b32_e32 v123, v4
	v_mov_b32_e32 v128, v4
	v_mov_b32_e32 v129, v4
	v_mov_b32_e32 v130, v4
	v_mov_b32_e32 v131, v4
	s_mov_b64 s[66:67], 0x80
	v_add_u32_e32 v221, 0x80, v2
	v_add_u32_e32 v220, 0x80, v136
	v_add_u32_e32 v219, 0x80, v132
	v_add_u32_e32 v218, 0x80, v134
.LBB0_1575:
	s_add_u32 s28, s26, 0xfffc0080
	s_addc_u32 s29, s27, -1
	s_add_i32 s60, 0, 0x10000
	s_cmp_eq_u32 s59, 12
	s_cselect_b32 s31, s19, s29
	s_cselect_b32 s30, s55, s28
	s_cselect_b32 s29, s17, s58
	s_cselect_b32 s28, s56, s57
	s_add_i32 s62, 0, 0x14000
	v_add_u32_e32 v158, s60, v147
	v_add_u32_e32 v174, s62, v147
	ds_read_b128 v[142:145], v158
	ds_read_b128 v[150:153], v158 offset:1024
	ds_read_b128 v[154:157], v158 offset:2048
	ds_read_b128 v[158:161], v158 offset:3072
	ds_read_b128 v[162:165], v174
	ds_read_b128 v[166:169], v174 offset:1024
	ds_read_b128 v[170:173], v174 offset:2048
	ds_read_b128 v[174:177], v174 offset:3072
	s_add_i32 m0, s47, 0xc000
	ds_read_b128 v[178:181], v149
	ds_read_b128 v[182:185], v149 offset:1024
	ds_read_b128 v[186:189], v149 offset:2048
	ds_read_b128 v[190:193], v149 offset:3072
	ds_read_b128 v[194:197], v149 offset:4096
	ds_read_b128 v[202:205], v149 offset:5120
	ds_read_b128 v[206:209], v149 offset:6144
	ds_read_b128 v[210:213], v149 offset:7168
	global_load_lds_dwordx4 v138, s[26:27]
	s_add_i32 m0, s47, 0xe000
	s_nop 0
	global_load_lds_dwordx4 v140, s[26:27]
	s_waitcnt vmcnt(8)
	s_waitcnt lgkmcnt(0)
	s_barrier
	s_setprio 1
	s_waitcnt lgkmcnt(0)
	v_mfma_f32_16x16x32_bf16 v[128:131], v[142:145], v[178:181], v[128:131]
	v_mfma_f32_16x16x32_bf16 v[120:123], v[154:157], v[178:181], v[120:123]
	v_mfma_f32_16x16x32_bf16 v[112:115], v[142:145], v[186:189], v[112:115]
	v_mfma_f32_16x16x32_bf16 v[104:107], v[154:157], v[186:189], v[104:107]
	v_mfma_f32_16x16x32_bf16 v[96:99], v[142:145], v[194:197], v[96:99]
	v_mfma_f32_16x16x32_bf16 v[88:91], v[154:157], v[194:197], v[88:91]
	v_mfma_f32_16x16x32_bf16 v[80:83], v[142:145], v[206:209], v[80:83]
	v_mfma_f32_16x16x32_bf16 v[72:75], v[154:157], v[206:209], v[72:75]
	v_mfma_f32_16x16x32_bf16 v[128:131], v[150:153], v[182:185], v[128:131]
	v_mfma_f32_16x16x32_bf16 v[120:123], v[158:161], v[182:185], v[120:123]
	v_mfma_f32_16x16x32_bf16 v[112:115], v[150:153], v[190:193], v[112:115]
	v_mfma_f32_16x16x32_bf16 v[104:107], v[158:161], v[190:193], v[104:107]
	v_mfma_f32_16x16x32_bf16 v[96:99], v[150:153], v[202:205], v[96:99]
	v_mfma_f32_16x16x32_bf16 v[88:91], v[158:161], v[202:205], v[88:91]
	v_mfma_f32_16x16x32_bf16 v[80:83], v[150:153], v[210:213], v[80:83]
	v_mfma_f32_16x16x32_bf16 v[72:75], v[158:161], v[210:213], v[72:75]
	s_setprio 0
	s_setprio 1
	v_mfma_f32_16x16x32_bf16 v[124:127], v[162:165], v[178:181], v[124:127]
	v_mfma_f32_16x16x32_bf16 v[116:119], v[170:173], v[178:181], v[116:119]
	v_mfma_f32_16x16x32_bf16 v[108:111], v[162:165], v[186:189], v[108:111]
	v_mfma_f32_16x16x32_bf16 v[100:103], v[170:173], v[186:189], v[100:103]
	v_mfma_f32_16x16x32_bf16 v[92:95], v[162:165], v[194:197], v[92:95]
	v_mfma_f32_16x16x32_bf16 v[84:87], v[170:173], v[194:197], v[84:87]
	v_mfma_f32_16x16x32_bf16 v[76:79], v[162:165], v[206:209], v[76:79]
	v_mfma_f32_16x16x32_bf16 v[68:71], v[170:173], v[206:209], v[68:71]
	v_mfma_f32_16x16x32_bf16 v[124:127], v[166:169], v[182:185], v[124:127]
	v_mfma_f32_16x16x32_bf16 v[116:119], v[174:177], v[182:185], v[116:119]
	v_mfma_f32_16x16x32_bf16 v[108:111], v[166:169], v[190:193], v[108:111]
	v_mfma_f32_16x16x32_bf16 v[100:103], v[174:177], v[190:193], v[100:103]
	v_mfma_f32_16x16x32_bf16 v[92:95], v[166:169], v[202:205], v[92:95]
	v_mfma_f32_16x16x32_bf16 v[84:87], v[174:177], v[202:205], v[84:87]
	v_mfma_f32_16x16x32_bf16 v[76:79], v[166:169], v[210:213], v[76:79]
	v_mfma_f32_16x16x32_bf16 v[68:71], v[174:177], v[210:213], v[68:71]
	s_setprio 0
	s_barrier
	s_add_i32 s60, s60, s46
	s_mov_b32 m0, s60
	ds_read_b128 v[178:181], v149 offset:16384
	ds_read_b128 v[182:185], v149 offset:17408
	ds_read_b128 v[186:189], v149 offset:18432
	ds_read_b128 v[190:193], v149 offset:19456
	ds_read_b128 v[194:197], v149 offset:20480
	ds_read_b128 v[202:205], v149 offset:21504
	ds_read_b128 v[206:209], v149 offset:22528
	ds_read_b128 v[210:213], v149 offset:23552
	global_load_lds_dwordx4 v2, s[28:29]
	s_add_i32 m0, s60, 0x2000
	s_add_u32 s60, s28, 0x40000
	s_mov_b64 s[98:99], s[28:29]
	s_addc_u32 s61, s29, 0
	s_add_i32 s62, s62, s46
	global_load_lds_dwordx4 v136, s[28:29]
	s_mov_b32 m0, s62
	s_mov_b64 s[100:101], s[30:31]
	global_load_lds_dwordx4 v2, s[60:61]
	s_add_i32 m0, s62, 0x2000
	s_nop 0
	global_load_lds_dwordx4 v136, s[60:61]
	s_mov_b32 m0, s47
	s_nop 0
	global_load_lds_dwordx4 v132, s[30:31]
	s_mov_b32 m0, s48
	s_nop 0
	global_load_lds_dwordx4 v134, s[30:31]
	s_waitcnt vmcnt(8)
	s_waitcnt lgkmcnt(0)
	s_barrier
	s_setprio 1
	s_waitcnt lgkmcnt(0)
	v_mfma_f32_16x16x32_bf16 v[64:67], v[142:145], v[178:181], v[64:67]
	v_mfma_f32_16x16x32_bf16 v[56:59], v[154:157], v[178:181], v[56:59]
	v_mfma_f32_16x16x32_bf16 v[48:51], v[142:145], v[186:189], v[48:51]
	v_mfma_f32_16x16x32_bf16 v[40:43], v[154:157], v[186:189], v[40:43]
	v_mfma_f32_16x16x32_bf16 v[32:35], v[142:145], v[194:197], v[32:35]
	v_mfma_f32_16x16x32_bf16 v[24:27], v[154:157], v[194:197], v[24:27]
	v_mfma_f32_16x16x32_bf16 v[16:19], v[142:145], v[206:209], v[16:19]
	v_mfma_f32_16x16x32_bf16 v[8:11], v[154:157], v[206:209], v[8:11]
	v_mfma_f32_16x16x32_bf16 v[64:67], v[150:153], v[182:185], v[64:67]
	v_mfma_f32_16x16x32_bf16 v[56:59], v[158:161], v[182:185], v[56:59]
	v_mfma_f32_16x16x32_bf16 v[48:51], v[150:153], v[190:193], v[48:51]
	v_mfma_f32_16x16x32_bf16 v[40:43], v[158:161], v[190:193], v[40:43]
	v_mfma_f32_16x16x32_bf16 v[32:35], v[150:153], v[202:205], v[32:35]
	v_mfma_f32_16x16x32_bf16 v[24:27], v[158:161], v[202:205], v[24:27]
	v_mfma_f32_16x16x32_bf16 v[16:19], v[150:153], v[210:213], v[16:19]
	v_mfma_f32_16x16x32_bf16 v[8:11], v[158:161], v[210:213], v[8:11]
	s_setprio 0
	s_setprio 1
	v_mfma_f32_16x16x32_bf16 v[60:63], v[162:165], v[178:181], v[60:63]
	v_mfma_f32_16x16x32_bf16 v[52:55], v[170:173], v[178:181], v[52:55]
	v_mfma_f32_16x16x32_bf16 v[44:47], v[162:165], v[186:189], v[44:47]
	v_mfma_f32_16x16x32_bf16 v[36:39], v[170:173], v[186:189], v[36:39]
	v_mfma_f32_16x16x32_bf16 v[28:31], v[162:165], v[194:197], v[28:31]
	v_mfma_f32_16x16x32_bf16 v[20:23], v[170:173], v[194:197], v[20:23]
	v_mfma_f32_16x16x32_bf16 v[12:15], v[162:165], v[206:209], v[12:15]
	v_mfma_f32_16x16x32_bf16 v[4:7], v[170:173], v[206:209], v[4:7]
	v_mfma_f32_16x16x32_bf16 v[60:63], v[166:169], v[182:185], v[60:63]
	v_mfma_f32_16x16x32_bf16 v[52:55], v[174:177], v[182:185], v[52:55]
	v_mfma_f32_16x16x32_bf16 v[44:47], v[166:169], v[190:193], v[44:47]
	v_mfma_f32_16x16x32_bf16 v[36:39], v[174:177], v[190:193], v[36:39]
	v_mfma_f32_16x16x32_bf16 v[28:31], v[166:169], v[202:205], v[28:31]
	v_mfma_f32_16x16x32_bf16 v[20:23], v[174:177], v[202:205], v[20:23]
	v_mfma_f32_16x16x32_bf16 v[12:15], v[166:169], v[210:213], v[12:15]
	v_mfma_f32_16x16x32_bf16 v[4:7], v[174:177], v[210:213], v[4:7]
	s_setprio 0
	s_barrier
	s_add_i32 s60, 0, 0x18000
	s_add_i32 s61, 0, 0x1c000
	v_add_u32_e32 v158, s60, v147
	v_add_u32_e32 v174, s61, v147
	ds_read_b128 v[142:145], v158
	ds_read_b128 v[150:153], v158 offset:1024
	ds_read_b128 v[154:157], v158 offset:2048
	ds_read_b128 v[158:161], v158 offset:3072
	ds_read_b128 v[162:165], v174
	ds_read_b128 v[166:169], v174 offset:1024
	ds_read_b128 v[170:173], v174 offset:2048
	ds_read_b128 v[174:177], v174 offset:3072
	s_add_u32 s30, s30, 0x40000
	s_addc_u32 s31, s31, 0
	s_mov_b32 m0, s49
	ds_read_b128 v[178:181], v149 offset:32768
	ds_read_b128 v[182:185], v149 offset:33792
	ds_read_b128 v[186:189], v149 offset:34816
	ds_read_b128 v[190:193], v149 offset:35840
	ds_read_b128 v[194:197], v149 offset:36864
	ds_read_b128 v[202:205], v149 offset:37888
	ds_read_b128 v[206:209], v149 offset:38912
	ds_read_b128 v[210:213], v149 offset:39936
	global_load_lds_dwordx4 v132, s[30:31]
	s_mov_b32 m0, s50
	s_nop 0
	global_load_lds_dwordx4 v134, s[30:31]
	s_waitcnt vmcnt(8)
	s_waitcnt lgkmcnt(0)
	s_barrier
	s_setprio 1
	s_waitcnt lgkmcnt(0)
	v_mfma_f32_16x16x32_bf16 v[128:131], v[142:145], v[178:181], v[128:131]
	v_mfma_f32_16x16x32_bf16 v[120:123], v[154:157], v[178:181], v[120:123]
	v_mfma_f32_16x16x32_bf16 v[112:115], v[142:145], v[186:189], v[112:115]
	v_mfma_f32_16x16x32_bf16 v[104:107], v[154:157], v[186:189], v[104:107]
	v_mfma_f32_16x16x32_bf16 v[96:99], v[142:145], v[194:197], v[96:99]
	v_mfma_f32_16x16x32_bf16 v[88:91], v[154:157], v[194:197], v[88:91]
	v_mfma_f32_16x16x32_bf16 v[80:83], v[142:145], v[206:209], v[80:83]
	v_mfma_f32_16x16x32_bf16 v[72:75], v[154:157], v[206:209], v[72:75]
	v_mfma_f32_16x16x32_bf16 v[128:131], v[150:153], v[182:185], v[128:131]
	v_mfma_f32_16x16x32_bf16 v[120:123], v[158:161], v[182:185], v[120:123]
	v_mfma_f32_16x16x32_bf16 v[112:115], v[150:153], v[190:193], v[112:115]
	v_mfma_f32_16x16x32_bf16 v[104:107], v[158:161], v[190:193], v[104:107]
	v_mfma_f32_16x16x32_bf16 v[96:99], v[150:153], v[202:205], v[96:99]
	v_mfma_f32_16x16x32_bf16 v[88:91], v[158:161], v[202:205], v[88:91]
	v_mfma_f32_16x16x32_bf16 v[80:83], v[150:153], v[210:213], v[80:83]
	v_mfma_f32_16x16x32_bf16 v[72:75], v[158:161], v[210:213], v[72:75]
	s_setprio 0
	s_setprio 1
	v_mfma_f32_16x16x32_bf16 v[124:127], v[162:165], v[178:181], v[124:127]
	v_mfma_f32_16x16x32_bf16 v[116:119], v[170:173], v[178:181], v[116:119]
	v_mfma_f32_16x16x32_bf16 v[108:111], v[162:165], v[186:189], v[108:111]
	v_mfma_f32_16x16x32_bf16 v[100:103], v[170:173], v[186:189], v[100:103]
	v_mfma_f32_16x16x32_bf16 v[92:95], v[162:165], v[194:197], v[92:95]
	v_mfma_f32_16x16x32_bf16 v[84:87], v[170:173], v[194:197], v[84:87]
	v_mfma_f32_16x16x32_bf16 v[76:79], v[162:165], v[206:209], v[76:79]
	v_mfma_f32_16x16x32_bf16 v[68:71], v[170:173], v[206:209], v[68:71]
	v_mfma_f32_16x16x32_bf16 v[124:127], v[166:169], v[182:185], v[124:127]
	v_mfma_f32_16x16x32_bf16 v[116:119], v[174:177], v[182:185], v[116:119]
	v_mfma_f32_16x16x32_bf16 v[108:111], v[166:169], v[190:193], v[108:111]
	v_mfma_f32_16x16x32_bf16 v[100:103], v[174:177], v[190:193], v[100:103]
	v_mfma_f32_16x16x32_bf16 v[92:95], v[166:169], v[202:205], v[92:95]
	v_mfma_f32_16x16x32_bf16 v[84:87], v[174:177], v[202:205], v[84:87]
	v_mfma_f32_16x16x32_bf16 v[76:79], v[166:169], v[210:213], v[76:79]
	v_mfma_f32_16x16x32_bf16 v[68:71], v[174:177], v[210:213], v[68:71]
	s_setprio 0
	s_barrier
	s_add_i32 s30, s60, s46
	s_mov_b32 m0, s30
	ds_read_b128 v[178:181], v149 offset:49152
	ds_read_b128 v[182:185], v149 offset:50176
	ds_read_b128 v[186:189], v149 offset:51200
	ds_read_b128 v[190:193], v149 offset:52224
	ds_read_b128 v[194:197], v149 offset:53248
	ds_read_b128 v[202:205], v149 offset:54272
	ds_read_b128 v[206:209], v149 offset:55296
	ds_read_b128 v[210:213], v149 offset:56320
	global_load_lds_dwordx4 v221, s[28:29]
	s_add_i32 m0, s30, 0x2000
	s_add_u32 s28, s28, 0x40080
	s_addc_u32 s29, s29, 0
	s_add_i32 s30, s61, s46
	global_load_lds_dwordx4 v220, s[98:99]
	s_mov_b32 m0, s30
	s_nop 0
	global_load_lds_dwordx4 v2, s[28:29]
	s_add_i32 m0, s30, 0x2000
	s_nop 0
	global_load_lds_dwordx4 v136, s[28:29]
	s_mov_b32 m0, s51
	s_nop 0
	global_load_lds_dwordx4 v219, s[100:101]
	s_mov_b32 m0, s52
	s_nop 0
	global_load_lds_dwordx4 v218, s[100:101]
	s_waitcnt vmcnt(8)
	s_waitcnt lgkmcnt(0)
	s_barrier
	s_setprio 1
	s_waitcnt lgkmcnt(0)
	v_mfma_f32_16x16x32_bf16 v[64:67], v[142:145], v[178:181], v[64:67]
	v_mfma_f32_16x16x32_bf16 v[56:59], v[154:157], v[178:181], v[56:59]
	v_mfma_f32_16x16x32_bf16 v[48:51], v[142:145], v[186:189], v[48:51]
	v_mfma_f32_16x16x32_bf16 v[40:43], v[154:157], v[186:189], v[40:43]
	v_mfma_f32_16x16x32_bf16 v[32:35], v[142:145], v[194:197], v[32:35]
	v_mfma_f32_16x16x32_bf16 v[24:27], v[154:157], v[194:197], v[24:27]
	v_mfma_f32_16x16x32_bf16 v[16:19], v[142:145], v[206:209], v[16:19]
	v_mfma_f32_16x16x32_bf16 v[8:11], v[154:157], v[206:209], v[8:11]
	v_mfma_f32_16x16x32_bf16 v[64:67], v[150:153], v[182:185], v[64:67]
	v_mfma_f32_16x16x32_bf16 v[56:59], v[158:161], v[182:185], v[56:59]
	v_mfma_f32_16x16x32_bf16 v[48:51], v[150:153], v[190:193], v[48:51]
	v_mfma_f32_16x16x32_bf16 v[40:43], v[158:161], v[190:193], v[40:43]
	v_mfma_f32_16x16x32_bf16 v[32:35], v[150:153], v[202:205], v[32:35]
	v_mfma_f32_16x16x32_bf16 v[24:27], v[158:161], v[202:205], v[24:27]
	v_mfma_f32_16x16x32_bf16 v[16:19], v[150:153], v[210:213], v[16:19]
	v_mfma_f32_16x16x32_bf16 v[8:11], v[158:161], v[210:213], v[8:11]
	s_setprio 0
	s_setprio 1
	v_mfma_f32_16x16x32_bf16 v[60:63], v[162:165], v[178:181], v[60:63]
	v_mfma_f32_16x16x32_bf16 v[52:55], v[170:173], v[178:181], v[52:55]
	v_mfma_f32_16x16x32_bf16 v[44:47], v[162:165], v[186:189], v[44:47]
	v_mfma_f32_16x16x32_bf16 v[36:39], v[170:173], v[186:189], v[36:39]
	v_mfma_f32_16x16x32_bf16 v[28:31], v[162:165], v[194:197], v[28:31]
	v_mfma_f32_16x16x32_bf16 v[20:23], v[170:173], v[194:197], v[20:23]
	v_mfma_f32_16x16x32_bf16 v[12:15], v[162:165], v[206:209], v[12:15]
	v_mfma_f32_16x16x32_bf16 v[4:7], v[170:173], v[206:209], v[4:7]
	v_mfma_f32_16x16x32_bf16 v[60:63], v[166:169], v[182:185], v[60:63]
	v_mfma_f32_16x16x32_bf16 v[52:55], v[174:177], v[182:185], v[52:55]
	v_mfma_f32_16x16x32_bf16 v[44:47], v[166:169], v[190:193], v[44:47]
	v_mfma_f32_16x16x32_bf16 v[36:39], v[174:177], v[190:193], v[36:39]
	v_mfma_f32_16x16x32_bf16 v[28:31], v[166:169], v[202:205], v[28:31]
	v_mfma_f32_16x16x32_bf16 v[20:23], v[174:177], v[202:205], v[20:23]
	v_mfma_f32_16x16x32_bf16 v[12:15], v[166:169], v[210:213], v[12:15]
	v_mfma_f32_16x16x32_bf16 v[4:7], v[174:177], v[210:213], v[4:7]
	s_setprio 0
	s_barrier
	s_add_i32 s59, s59, 2
	s_add_u32 s26, s26, 0x100
	s_addc_u32 s27, s27, 0
	s_add_u32 s57, s57, 0x100
	s_addc_u32 s58, s58, 0
	s_cmp_gt_u32 s59, 13
	s_cbranch_scc0 .LBB0_1575
	s_and_b64 vcc, exec, s[14:15]
	s_mov_b64 s[58:59], 0x9300380
	s_cbranch_vccz .LBB0_1578
	s_barrier
